# v14 + decode K loads without the nt hint (pairs of half-line loads can merge in L1)
# speedup vs baseline: 1.0107x; 1.0090x over previous
.LBB0_1241:
	s_or_b64 exec, exec, s[10:11]
	s_lshl_b32 s0, s13, 2
	s_and_b32 s0, s0, -16
	s_ashr_i32 s1, s0, 31
	s_lshl_b32 s14, s43, 7
	s_and_b32 s15, s42, 7
	s_lshl_b64 s[0:1], s[0:1], 2
	s_add_u32 s0, s60, s0
	s_addc_u32 s1, s61, s1
	s_lshl_b32 s10, s15, 3
	v_mov_b32_e32 v2, s10
	global_load_dword v4, v2, s[0:1]
	v_lshlrev_b32_e32 v5, 13, v139
	v_lshl_or_b32 v6, v123, 4, v5
	s_lshl_b32 s13, s14, 2
	v_lshlrev_b32_e32 v2, 5, v139
	v_mov_b32_e32 v7, v3
	v_lshl_add_u32 v2, v123, 11, v2
	s_lshl_b32 s10, s43, 9
	v_lshlrev_b32_e32 v124, 2, v139
	v_lshl_add_u64 v[128:129], s[56:57], 0, v[2:3]
	s_lshl_b32 s22, s15, 8
	s_add_i32 s43, s10, 0
	v_lshl_add_u64 v[130:131], s[58:59], 0, v[6:7]
	v_sub_u32_e32 v141, v125, v124
	s_add_i32 s43, s43, 0x26a00
	s_waitcnt vmcnt(4)
	v_subrev_u32_e32 v142, s22, v141
	s_mov_b32 s68, 0
	v_mov_b32_e32 v138, 0
	v_mov_b32_e32 v140, 0xf149f2ca
	s_mov_b32 s69, 16
	s_waitcnt vmcnt(0)
	v_ashrrev_i32_e32 v5, 31, v4
	v_lshlrev_b64 v[4:5], 18, v[4:5]
	v_or_b32_e32 v4, s13, v4
	v_lshl_add_u64 v[8:9], s[56:57], 0, v[4:5]
	v_lshl_add_u64 v[4:5], s[58:59], 0, v[4:5]
	v_lshl_add_u64 v[8:9], v[8:9], 0, v[2:3]
	v_lshl_add_u64 v[4:5], v[4:5], 0, v[6:7]
	v_lshl_add_u64 v[10:11], v[4:5], 0, s[38:39]
	global_load_dwordx4 v[52:55], v[8:9], off offset:16
	global_load_dwordx4 v[56:59], v[8:9], off
	global_load_dwordx4 v[60:63], v[8:9], off offset:144
	global_load_dwordx4 v[64:67], v[8:9], off offset:128
	global_load_dwordx4 v[68:71], v[8:9], off offset:272
	global_load_dwordx4 v[72:75], v[8:9], off offset:256
	global_load_dwordx4 v[76:79], v[8:9], off offset:400
	global_load_dwordx4 v[80:83], v[8:9], off offset:384
	global_load_dwordx4 v[84:87], v[4:5], off nt
	global_load_dwordx4 v[88:91], v[4:5], off offset:256 nt
	global_load_dwordx4 v[92:95], v[4:5], off offset:2048 nt
	global_load_dwordx4 v[96:99], v[4:5], off offset:2304 nt
	global_load_dwordx4 v[100:103], v[10:11], off nt
	global_load_dwordx4 v[104:107], v[10:11], off offset:256 nt
	global_load_dwordx4 v[108:111], v[10:11], off offset:2048 nt
	global_load_dwordx4 v[112:115], v[10:11], off offset:2304 nt
	v_mov_b32_e32 v4, v3
	v_mov_b32_e32 v5, v3
	v_mov_b32_e32 v2, v3
	v_mov_b64_e32 v[22:23], v[4:5]
	v_mov_b64_e32 v[30:31], v[4:5]
	v_mov_b64_e32 v[34:35], v[4:5]
	v_mov_b64_e32 v[26:27], v[4:5]
	v_mov_b64_e32 v[10:11], v[4:5]
	v_mov_b64_e32 v[14:15], v[4:5]
	v_mov_b64_e32 v[18:19], v[4:5]
	v_mov_b64_e32 v[20:21], v[2:3]
	v_mov_b64_e32 v[28:29], v[2:3]
	v_mov_b64_e32 v[32:33], v[2:3]
	v_mov_b64_e32 v[24:25], v[2:3]
	v_mov_b64_e32 v[8:9], v[2:3]
	v_mov_b64_e32 v[12:13], v[2:3]
	v_mov_b64_e32 v[16:17], v[2:3]
	v_mov_b64_e32 v[6:7], v[4:5]
	v_mov_b64_e32 v[4:5], v[2:3]
	s_branch .LBB0_1243

.LBB0_1247:
	v_lshlrev_b64 v[132:133], 9, v[116:117]
	v_or_b32_e32 v132, s14, v132
	v_lshl_add_u64 v[148:149], v[132:133], 2, v[128:129]
	s_waitcnt vmcnt(14)
	v_cvt_pk_bf16_f32 v116, v56, v57
	v_cvt_pk_bf16_f32 v117, v58, v59
	v_cvt_pk_bf16_f32 v118, v52, v53
	v_cvt_pk_bf16_f32 v119, v54, v55
	global_load_dwordx4 v[52:55], v[148:149], off offset:16
	global_load_dwordx4 v[56:59], v[148:149], off
	v_mfma_f32_16x16x32_bf16 v[116:119], v[116:119], v[48:51], 0
	s_waitcnt vmcnt(14)
	v_cvt_pk_bf16_f32 v144, v64, v65
	v_cvt_pk_bf16_f32 v145, v66, v67
	v_cvt_pk_bf16_f32 v146, v60, v61
	v_cvt_pk_bf16_f32 v147, v62, v63
	global_load_dwordx4 v[60:63], v[148:149], off offset:144
	global_load_dwordx4 v[64:67], v[148:149], off offset:128
	v_mfma_f32_16x16x32_bf16 v[116:119], v[144:147], v[40:43], v[116:119]
	s_waitcnt vmcnt(14)
	v_cvt_pk_bf16_f32 v144, v72, v73
	v_cvt_pk_bf16_f32 v145, v74, v75
	v_cvt_pk_bf16_f32 v146, v68, v69
	v_cvt_pk_bf16_f32 v147, v70, v71
	global_load_dwordx4 v[68:71], v[148:149], off offset:272
	global_load_dwordx4 v[72:75], v[148:149], off offset:256
	v_mfma_f32_16x16x32_bf16 v[116:119], v[144:147], v[44:47], v[116:119]
	s_waitcnt vmcnt(14)
	v_cvt_pk_bf16_f32 v144, v80, v81
	v_cvt_pk_bf16_f32 v145, v82, v83
	v_cvt_pk_bf16_f32 v146, v76, v77
	v_cvt_pk_bf16_f32 v147, v78, v79
	global_load_dwordx4 v[76:79], v[148:149], off offset:400
	global_load_dwordx4 v[80:83], v[148:149], off offset:384
	v_mfma_f32_16x16x32_bf16 v[116:119], v[144:147], v[36:39], v[116:119]
	s_cmpk_lt_u32 s10, 0x780
	s_cbranch_scc1 .LBB0_1249
	v_add_u32_e32 v2, s68, v142
	v_add_u32_e32 v144, 0x7ff, v2
	v_min_i32_e32 v144, 0x7f, v144
	v_add_u32_e32 v143, 0x800, v2
	v_lshl_add_u32 v145, v144, 2, s43
	v_add_u32_e32 v144, 0x7fe, v2
	v_min_i32_e32 v143, 0x7f, v143
	v_min_i32_e32 v144, 0x7f, v144
	v_add_u32_e32 v2, 0x7fd, v2
	v_lshl_add_u32 v143, v143, 2, s43
	v_lshl_add_u32 v146, v144, 2, s43
	v_min_i32_e32 v2, 0x7f, v2
	v_lshl_add_u32 v2, v2, 2, s43
	ds_read_b32 v144, v143
	ds_read_b32 v146, v146
	ds_read_b32 v147, v2
	ds_read_b32 v145, v145
	s_waitcnt lgkmcnt(1)
	v_pk_add_f32 v[118:119], v[118:119], v[146:147]
	s_waitcnt lgkmcnt(0)
	v_pk_add_f32 v[116:117], v[116:117], v[144:145]
